# v23b: v15 + int8 GEMM output stores as full 128-byte lines (B-tile column blocks of a wave made adjacent, packed results exchanged between lanes l and l^8 by DPP so each store covers 8 rows x 128 B)
# baseline (speedup 1.0000x reference)
.LBB0_299:
	s_andn2_b64 vcc, exec, s[6:7]
	s_cbranch_vccnz .LBB0_368
	s_mov_b32 s36, s2
	s_mov_b32 s4, s76
	s_mov_b64 s[6:7], s[72:73]
	s_mov_b32 s37, s89
	s_mov_b64 s[12:13], s[74:75]
	v_mbcnt_lo_u32_b32 v0, -1, 0
	v_mbcnt_hi_u32_b32 v0, -1, v0
	v_mbcnt_lo_u32_b32 v14, -1, 0
	v_mbcnt_hi_u32_b32 v14, -1, v14
	s_cmpk_gt_i32 s36, 0x1397
	v_lshl_add_u32 v0, s4, 6, v14
	s_nop 0
	v_readfirstlane_b32 s14, v0
	s_cbranch_scc1 .LBB0_316
	v_lshlrev_b32_e32 v1, 4, v0
	v_add_u32_e32 v2, 0x2000, v1
	v_ashrrev_i32_e32 v3, 31, v2
	v_lshrrev_b32_e32 v3, 22, v3
	v_add_u32_e32 v3, v2, v3
	v_ashrrev_i32_e32 v8, 10, v3
	v_mul_i32_i24_e32 v3, 0x400, v8
	v_sub_u32_e32 v2, v2, v3
	v_lshrrev_b32_e32 v3, 4, v2
	v_bitop3_b32 v2, v3, v2, 32 bitop3:0x6c
	v_ashrrev_i32_e32 v3, 31, v2
	v_lshrrev_b32_e32 v3, 26, v3
	v_add_u32_e32 v3, v2, v3
	v_lshlrev_b32_e32 v4, 3, v8
	v_ashrrev_i32_e32 v9, 6, v3
	v_and_b32_e32 v4, -16, v4
	v_add_u32_e32 v4, v9, v4
	v_and_b32_e32 v5, 3, v9
	s_mov_b32 s4, 0x1fffe0
	v_lshrrev_b32_e32 v6, 2, v4
	v_lshlrev_b32_e32 v7, 1, v4
	v_and_b32_e32 v3, 0xc0, v3
	v_and_or_b32 v5, v4, s4, v5
	v_and_b32_e32 v6, 4, v6
	v_and_b32_e32 v7, 24, v7
	v_sub_u32_e32 v2, v2, v3
	v_or3_b32 v5, v5, v6, v7
	v_and_b32_e32 v6, -32, v4
	v_add_u32_e32 v5, v5, v6
	v_lshlrev_b32_e32 v6, 5, v8
	v_ashrrev_i16_sdwa v2, v239, sext(v2) dst_sel:DWORD dst_unused:UNUSED_PAD src0_sel:DWORD src1_sel:BYTE_0
	v_and_b32_e32 v6, 32, v6
	v_bfe_i32 v10, v2, 0, 16
	v_add_lshl_u32 v2, v6, v10, 1
	v_lshl_add_u32 v146, v5, 11, v2
	v_lshl_add_u32 v148, v4, 11, v2
	v_bfe_i32 v2, v0, 27, 1
	v_lshrrev_b32_e32 v2, 22, v2
	v_add_u32_e32 v2, v1, v2
	v_and_b32_e32 v2, 0xfffffc00, v2
	v_sub_u32_e32 v1, v1, v2
	v_lshrrev_b32_e32 v2, 4, v1
	v_ashrrev_i32_e32 v3, 31, v0
	v_bitop3_b32 v1, v2, v1, 32 bitop3:0x6c
	v_lshrrev_b32_e32 v3, 26, v3
	v_ashrrev_i32_e32 v2, 31, v1
	v_add_u32_e32 v0, v0, v3
	s_add_u32 s38, s12, 0xe4b4000
	v_lshrrev_b32_e32 v2, 26, v2
	v_ashrrev_i32_e32 v12, 6, v0
	s_addc_u32 s39, s13, 0
	v_add_u32_e32 v2, v1, v2
	v_lshlrev_b32_e32 v0, 3, v12
	s_add_u32 s54, s12, 0x30b4000
	v_ashrrev_i32_e32 v11, 6, v2
	v_and_b32_e32 v0, -16, v0
	s_addc_u32 s55, s13, 0
	v_add_u32_e32 v0, v11, v0
	v_and_b32_e32 v3, 3, v11
	s_ashr_i32 s34, s36, 31
	v_and_or_b32 v3, v0, s4, v3
	s_lshr_b32 s4, s34, 29
	s_add_i32 s4, s36, s4
	s_ashr_i32 s15, s14, 6
	s_ashr_i32 s6, s4, 3
	s_and_b32 s4, s4, -8
	s_ashr_i32 s16, s14, 8
	s_lshl_b32 s56, s15, 10
	s_sub_i32 s4, s36, s4
	s_cmp_lt_i32 s4, 0
	s_movk_i32 s7, 0x274
	s_cselect_b32 s7, s7, 0x273
	s_mul_i32 s4, s4, s7
	s_add_i32 s4, s4, s6
	s_mul_hi_i32 s6, s4, 0x8fb823ef
	s_add_i32 s6, s6, s4
	s_lshr_b32 s7, s6, 31
	s_ashr_i32 s6, s6, 7
	s_add_i32 s6, s6, s7
	s_mul_i32 s7, s6, 3
	s_mulk_i32 s6, 0xe4
	s_sub_i32 s6, s4, s6
	s_mul_i32 s4, s6, 0x5556
	s_lshr_b32 s8, s4, 31
	s_lshr_b32 s4, s4, 16
	s_add_i32 s4, s4, s8
	s_mul_i32 s8, s4, 3
	s_sub_i32 s6, s6, s8
	s_sext_i32_i16 s6, s6
	s_add_i32 s7, s7, s6
	v_lshrrev_b32_e32 v4, 2, v0
	v_lshlrev_b32_e32 v5, 1, v0
	v_and_b32_e32 v2, 0xc0, v2
	s_lshl_b32 s46, s7, 1
	v_and_b32_e32 v4, 4, v4
	v_and_b32_e32 v5, 24, v5
	v_sub_u32_e32 v1, v1, v2
	s_ashr_i32 s47, s46, 31
	s_bfe_i64 s[8:9], s[4:5], 0x100000
	v_or3_b32 v3, v3, v4, v5
	v_and_b32_e32 v4, -32, v0
	v_add_u32_e32 v3, v3, v4
	v_lshlrev_b32_e32 v4, 5, v12
	v_ashrrev_i16_sdwa v1, v239, sext(v1) dst_sel:DWORD dst_unused:UNUSED_PAD src0_sel:DWORD src1_sel:BYTE_0
	s_lshl_b64 s[6:7], s[46:47], 18
	s_lshl_b64 s[8:9], s[8:9], 19
	v_and_b32_e32 v4, 32, v4
	v_bfe_i32 v13, v1, 0, 16
	s_add_u32 s50, s54, s8
	v_add_lshl_u32 v1, v4, v13, 1
	s_addc_u32 s51, s55, s9
	s_add_i32 s35, s56, 0
	v_lshl_add_u32 v150, v3, 11, v1
	s_add_i32 m0, s35, 0x10000
	v_lshl_add_u32 v152, v0, 11, v1
	global_load_lds_dwordx4 v150, s[50:51]
	s_add_i32 m0, s35, 0x12000
	s_add_u32 s8, s50, 0x10000
	global_load_lds_dwordx4 v146, s[50:51]
	s_addc_u32 s9, s51, 0
	s_add_i32 m0, s35, 0x14000
	v_mov_b32_e32 v151, v96
	global_load_lds_dwordx4 v150, s[8:9]
	s_add_i32 m0, s35, 0x16000
	s_add_u32 s48, s38, s6
	s_addc_u32 s49, s39, s7
	s_add_i32 s57, s35, 0x2000
	global_load_lds_dwordx4 v146, s[8:9]
	s_mov_b32 m0, s35
	s_add_u32 s6, s48, 0x40000
	global_load_lds_dwordx4 v152, s[48:49]
	s_mov_b32 m0, s57
	s_addc_u32 s7, s49, 0
	s_add_i32 s58, s35, 0x4000
	global_load_lds_dwordx4 v148, s[48:49]
	s_mov_b32 m0, s58
	s_add_i32 s59, s35, 0x6000
	global_load_lds_dwordx4 v152, s[6:7]
	s_mov_b32 m0, s59
	v_mov_b32_e32 v147, v96
	global_load_lds_dwordx4 v148, s[6:7]
	v_mov_b32_e32 v153, v96
	v_mov_b32_e32 v149, v96
	s_cmp_eq_u32 s16, 1
	v_lshl_add_u64 v[6:7], s[50:51], 0, v[150:151]
	v_lshl_add_u64 v[4:5], s[50:51], 0, v[146:147]
	v_lshl_add_u64 v[0:1], s[48:49], 0, v[152:153]
	s_cselect_b64 s[6:7], -1, 0
	s_cmp_lg_u32 s16, 1
	v_lshl_add_u64 v[2:3], s[48:49], 0, v[148:149]
	s_cbranch_scc1 .LBB0_303
	s_barrier
.LBB0_303:
	s_add_u32 s8, s12, 0x1aab4000
	s_addc_u32 s9, s13, 0
	s_add_u32 s10, s12, 0x5b87000
	v_lshrrev_b32_e32 v16, 1, v14
	s_addc_u32 s11, s13, 0
	v_and_b32_e32 v16, 24, v16
	s_add_u32 s12, s12, 0x5b74000
	v_and_b32_e32 v15, 15, v14
	v_lshlrev_b32_e32 v17, 1, v16
	v_lshlrev_b32_e32 v14, 2, v14
	s_sext_i32_i16 s47, s4
	s_addc_u32 s13, s13, 0
	v_lshl_or_b32 v97, s16, 6, v15
	v_lshl_or_b32 v15, v15, 6, v17
	s_lshl_b32 s4, s16, 13
	v_and_b32_e32 v14, 32, v14
	v_bitop3_b32 v17, v15, s4, v14 bitop3:0xde
	s_lshl_b32 s4, s15, 5
	s_and_b32 s18, s4, 0x60
	s_lshl_b32 s4, s18, 7
	s_add_i32 m0, s35, 0x18000
	v_lshl_add_u64 v[6:7], v[6:7], 0, s[90:91]
	v_bitop3_b32 v167, v15, s4, v14 bitop3:0xde
	s_waitcnt vmcnt(2)
	s_barrier
	global_load_lds_dwordx4 v[6:7], off
	v_lshl_add_u64 v[4:5], v[4:5], 0, s[90:91]
	s_add_i32 m0, s35, 0x1a000
	s_add_i32 s4, s35, 0x8000
	s_add_i32 s60, s35, 0xa000
	global_load_lds_dwordx4 v[4:5], off
	v_lshl_add_u64 v[0:1], v[0:1], 0, s[90:91]
	s_mov_b32 m0, s4
	s_add_u32 s16, s50, 0x10080
	global_load_lds_dwordx4 v[0:1], off
	v_lshl_add_u64 v[0:1], v[2:3], 0, s[90:91]
	s_mov_b32 m0, s60
	s_addc_u32 s17, s51, 0
	global_load_lds_dwordx4 v[0:1], off
	s_add_i32 m0, s35, 0x1c000
	v_lshl_add_u64 v[0:1], s[16:17], 0, v[150:151]
	global_load_lds_dwordx4 v[0:1], off
	v_lshl_add_u64 v[0:1], s[16:17], 0, v[146:147]
	s_add_i32 m0, s35, 0x1e000
	s_cmpk_lt_u32 s14, 0x100
	global_load_lds_dwordx4 v[0:1], off
	v_lshlrev_b32_e32 v0, 14, v12
	v_and_b32_e32 v0, 0xffff8000, v0
	v_lshl_add_u32 v0, v11, 11, v0
	v_and_b32_e32 v1, 1, v12
	v_lshl_or_b32 v0, v1, 6, v0
	v_lshl_add_u32 v154, v13, 1, v0
	v_lshlrev_b32_e32 v0, 14, v8
	v_and_b32_e32 v0, 0xffff8000, v0
	s_waitcnt vmcnt(6)
	v_lshl_add_u32 v0, v9, 11, v0
	v_and_b32_e32 v1, 1, v8
	v_lshl_or_b32 v0, v1, 6, v0
	s_cselect_b64 s[14:15], -1, 0
	s_ashr_i32 s61, s37, 31
	v_or_b32_e32 v168, s18, v16
	v_add_u32_e32 v168, s18, v168
	v_mov_b32_e32 v155, v96
	v_lshl_add_u32 v156, v10, 1, v0
	v_mov_b32_e32 v157, v96
	s_mov_b32 s62, 0
	v_add_u32_e32 v169, 0, v17
	s_barrier
	s_branch .LBB0_306

.LBB0_309:
	s_add_u32 s26, s48, 0xfffc0080
	s_addc_u32 s27, s49, -1
	s_add_i32 s68, 0, 0x10000
	s_cmp_eq_u32 s67, 12
	s_cselect_b32 s53, s19, s27
	s_cselect_b32 s52, s63, s26
	s_cselect_b32 s51, s17, s66
	s_cselect_b32 s50, s64, s65
	s_add_i32 s69, 0, 0x14000
	v_add_u32_e32 v72, s68, v167
	v_add_u32_e32 v166, s69, v167
	ds_read_b128 v[56:59], v72
	ds_read_b128 v[60:63], v72 offset:1024
	ds_read_b128 v[68:71], v72 offset:2048
	ds_read_b128 v[72:75], v72 offset:3072
	ds_read_b128 v[158:161], v166
	ds_read_b128 v[162:165], v166 offset:1024
	ds_read_b128 v[170:173], v166 offset:2048
	ds_read_b128 v[174:177], v166 offset:3072
	v_lshl_add_u64 v[214:215], s[48:49], 0, v[154:155]
	s_add_i32 m0, s35, 0xc000
	ds_read_b128 v[178:181], v169
	ds_read_b128 v[182:185], v169 offset:1024
	ds_read_b128 v[186:189], v169 offset:2048
	ds_read_b128 v[190:193], v169 offset:3072
	ds_read_b128 v[198:201], v169 offset:4096
	ds_read_b128 v[202:205], v169 offset:5120
	ds_read_b128 v[206:209], v169 offset:6144
	ds_read_b128 v[210:213], v169 offset:7168
	global_load_lds_dwordx4 v[214:215], off
	v_lshl_add_u64 v[214:215], s[48:49], 0, v[156:157]
	s_add_i32 m0, s35, 0xe000
	s_nop 0
	global_load_lds_dwordx4 v[214:215], off
	s_waitcnt vmcnt(8)
	s_waitcnt lgkmcnt(0)
	s_barrier
	s_setprio 1
	s_waitcnt lgkmcnt(0)
	v_mfma_i32_16x16x64_i8 v[142:145], v[56:59], v[178:181], v[142:145]
	v_mfma_i32_16x16x64_i8 v[138:141], v[68:71], v[178:181], v[138:141]
	v_mfma_i32_16x16x64_i8 v[126:129], v[56:59], v[186:189], v[126:129]
	v_mfma_i32_16x16x64_i8 v[122:125], v[68:71], v[186:189], v[122:125]
	v_mfma_i32_16x16x64_i8 v[110:113], v[56:59], v[198:201], v[110:113]
	v_mfma_i32_16x16x64_i8 v[106:109], v[68:71], v[198:201], v[106:109]
	v_mfma_i32_16x16x64_i8 v[92:95], v[56:59], v[206:209], v[92:95]
	v_mfma_i32_16x16x64_i8 v[88:91], v[68:71], v[206:209], v[88:91]
	v_mfma_i32_16x16x64_i8 v[142:145], v[60:63], v[182:185], v[142:145]
	v_mfma_i32_16x16x64_i8 v[138:141], v[72:75], v[182:185], v[138:141]
	v_mfma_i32_16x16x64_i8 v[126:129], v[60:63], v[190:193], v[126:129]
	v_mfma_i32_16x16x64_i8 v[122:125], v[72:75], v[190:193], v[122:125]
	v_mfma_i32_16x16x64_i8 v[110:113], v[60:63], v[202:205], v[110:113]
	v_mfma_i32_16x16x64_i8 v[106:109], v[72:75], v[202:205], v[106:109]
	v_mfma_i32_16x16x64_i8 v[92:95], v[60:63], v[210:213], v[92:95]
	v_mfma_i32_16x16x64_i8 v[88:91], v[72:75], v[210:213], v[88:91]
	s_setprio 0
	s_setprio 1
	v_mfma_i32_16x16x64_i8 v[134:137], v[158:161], v[178:181], v[134:137]
	v_mfma_i32_16x16x64_i8 v[130:133], v[170:173], v[178:181], v[130:133]
	v_mfma_i32_16x16x64_i8 v[118:121], v[158:161], v[186:189], v[118:121]
	v_mfma_i32_16x16x64_i8 v[114:117], v[170:173], v[186:189], v[114:117]
	v_mfma_i32_16x16x64_i8 v[102:105], v[158:161], v[198:201], v[102:105]
	v_mfma_i32_16x16x64_i8 v[98:101], v[170:173], v[198:201], v[98:101]
	v_mfma_i32_16x16x64_i8 v[84:87], v[158:161], v[206:209], v[84:87]
	v_mfma_i32_16x16x64_i8 v[80:83], v[170:173], v[206:209], v[80:83]
	v_mfma_i32_16x16x64_i8 v[134:137], v[162:165], v[182:185], v[134:137]
	v_mfma_i32_16x16x64_i8 v[130:133], v[174:177], v[182:185], v[130:133]
	v_mfma_i32_16x16x64_i8 v[118:121], v[162:165], v[190:193], v[118:121]
	v_mfma_i32_16x16x64_i8 v[114:117], v[174:177], v[190:193], v[114:117]
	v_mfma_i32_16x16x64_i8 v[102:105], v[162:165], v[202:205], v[102:105]
	v_mfma_i32_16x16x64_i8 v[98:101], v[174:177], v[202:205], v[98:101]
	v_mfma_i32_16x16x64_i8 v[84:87], v[162:165], v[210:213], v[84:87]
	v_mfma_i32_16x16x64_i8 v[80:83], v[174:177], v[210:213], v[80:83]
	s_setprio 0
	s_barrier
	s_add_i32 s26, s68, s56
	v_lshl_add_u64 v[214:215], s[50:51], 0, v[150:151]
	s_mov_b32 m0, s26
	ds_read_b128 v[178:181], v169 offset:16384
	ds_read_b128 v[182:185], v169 offset:17408
	ds_read_b128 v[186:189], v169 offset:18432
	ds_read_b128 v[190:193], v169 offset:19456
	ds_read_b128 v[198:201], v169 offset:20480
	ds_read_b128 v[202:205], v169 offset:21504
	ds_read_b128 v[206:209], v169 offset:22528
	ds_read_b128 v[210:213], v169 offset:23552
	global_load_lds_dwordx4 v[214:215], off
	s_add_i32 m0, s26, 0x2000
	s_add_u32 s26, s50, 0x10000
	v_lshl_add_u64 v[216:217], s[50:51], 0, v[146:147]
	s_addc_u32 s27, s51, 0
	s_add_i32 s68, s69, s56
	global_load_lds_dwordx4 v[216:217], off
	v_lshl_add_u64 v[218:219], s[26:27], 0, v[150:151]
	s_mov_b32 m0, s68
	v_lshl_add_u64 v[220:221], s[52:53], 0, v[148:149]
	global_load_lds_dwordx4 v[218:219], off
	v_lshl_add_u64 v[218:219], s[26:27], 0, v[146:147]
	s_add_i32 m0, s68, 0x2000
	s_nop 0
	global_load_lds_dwordx4 v[218:219], off
	v_lshl_add_u64 v[218:219], s[52:53], 0, v[152:153]
	s_mov_b32 m0, s35
	s_nop 0
	global_load_lds_dwordx4 v[218:219], off
	s_mov_b32 m0, s57
	s_nop 0
	global_load_lds_dwordx4 v[220:221], off
	s_waitcnt vmcnt(8)
	s_waitcnt lgkmcnt(0)
	s_barrier
	s_setprio 1
	s_waitcnt lgkmcnt(0)
	v_mfma_i32_16x16x64_i8 v[76:79], v[56:59], v[178:181], v[76:79]
	v_mfma_i32_16x16x64_i8 v[64:67], v[68:71], v[178:181], v[64:67]
	v_mfma_i32_16x16x64_i8 v[44:47], v[56:59], v[186:189], v[44:47]
	v_mfma_i32_16x16x64_i8 v[40:43], v[68:71], v[186:189], v[40:43]
	v_mfma_i32_16x16x64_i8 v[28:31], v[56:59], v[198:201], v[28:31]
	v_mfma_i32_16x16x64_i8 v[24:27], v[68:71], v[198:201], v[24:27]
	v_mfma_i32_16x16x64_i8 v[12:15], v[56:59], v[206:209], v[12:15]
	v_mfma_i32_16x16x64_i8 v[8:11], v[68:71], v[206:209], v[8:11]
	v_mfma_i32_16x16x64_i8 v[76:79], v[60:63], v[182:185], v[76:79]
	v_mfma_i32_16x16x64_i8 v[64:67], v[72:75], v[182:185], v[64:67]
	v_mfma_i32_16x16x64_i8 v[44:47], v[60:63], v[190:193], v[44:47]
	v_mfma_i32_16x16x64_i8 v[40:43], v[72:75], v[190:193], v[40:43]
	v_mfma_i32_16x16x64_i8 v[28:31], v[60:63], v[202:205], v[28:31]
	v_mfma_i32_16x16x64_i8 v[24:27], v[72:75], v[202:205], v[24:27]
	v_mfma_i32_16x16x64_i8 v[12:15], v[60:63], v[210:213], v[12:15]
	v_mfma_i32_16x16x64_i8 v[8:11], v[72:75], v[210:213], v[8:11]
	s_setprio 0
	s_setprio 1
	v_mfma_i32_16x16x64_i8 v[52:55], v[158:161], v[178:181], v[52:55]
	v_mfma_i32_16x16x64_i8 v[48:51], v[170:173], v[178:181], v[48:51]
	v_mfma_i32_16x16x64_i8 v[36:39], v[158:161], v[186:189], v[36:39]
	v_mfma_i32_16x16x64_i8 v[32:35], v[170:173], v[186:189], v[32:35]
	v_mfma_i32_16x16x64_i8 v[20:23], v[158:161], v[198:201], v[20:23]
	v_mfma_i32_16x16x64_i8 v[16:19], v[170:173], v[198:201], v[16:19]
	v_mfma_i32_16x16x64_i8 v[4:7], v[158:161], v[206:209], v[4:7]
	v_mfma_i32_16x16x64_i8 v[0:3], v[170:173], v[206:209], v[0:3]
	v_mfma_i32_16x16x64_i8 v[52:55], v[162:165], v[182:185], v[52:55]
	v_mfma_i32_16x16x64_i8 v[48:51], v[174:177], v[182:185], v[48:51]
	v_mfma_i32_16x16x64_i8 v[36:39], v[162:165], v[190:193], v[36:39]
	v_mfma_i32_16x16x64_i8 v[32:35], v[174:177], v[190:193], v[32:35]
	v_mfma_i32_16x16x64_i8 v[20:23], v[162:165], v[202:205], v[20:23]
	v_mfma_i32_16x16x64_i8 v[16:19], v[174:177], v[202:205], v[16:19]
	v_mfma_i32_16x16x64_i8 v[4:7], v[162:165], v[210:213], v[4:7]
	v_mfma_i32_16x16x64_i8 v[0:3], v[174:177], v[210:213], v[0:3]
	s_setprio 0
	s_barrier
	s_add_i32 s68, 0, 0x18000
	s_add_i32 s69, 0, 0x1c000
	v_add_u32_e32 v72, s68, v167
	v_add_u32_e32 v166, s69, v167
	ds_read_b128 v[56:59], v72
	ds_read_b128 v[60:63], v72 offset:1024
	ds_read_b128 v[68:71], v72 offset:2048
	ds_read_b128 v[72:75], v72 offset:3072
	ds_read_b128 v[158:161], v166
	ds_read_b128 v[162:165], v166 offset:1024
	ds_read_b128 v[170:173], v166 offset:2048
	ds_read_b128 v[174:177], v166 offset:3072
	s_add_u32 s26, s52, 0x40000
	s_addc_u32 s27, s53, 0
	s_mov_b32 m0, s58
	v_lshl_add_u64 v[222:223], s[26:27], 0, v[152:153]
	ds_read_b128 v[178:181], v169 offset:32768
	ds_read_b128 v[182:185], v169 offset:33792
	ds_read_b128 v[186:189], v169 offset:34816
	ds_read_b128 v[190:193], v169 offset:35840
	ds_read_b128 v[198:201], v169 offset:36864
	ds_read_b128 v[202:205], v169 offset:37888
	ds_read_b128 v[206:209], v169 offset:38912
	ds_read_b128 v[210:213], v169 offset:39936
	global_load_lds_dwordx4 v[222:223], off
	v_lshl_add_u64 v[222:223], s[26:27], 0, v[148:149]
	s_mov_b32 m0, s59
	s_nop 0
	global_load_lds_dwordx4 v[222:223], off
	s_waitcnt vmcnt(8)
	s_waitcnt lgkmcnt(0)
	s_barrier
	s_setprio 1
	s_waitcnt lgkmcnt(0)
	v_mfma_i32_16x16x64_i8 v[142:145], v[56:59], v[178:181], v[142:145]
	v_mfma_i32_16x16x64_i8 v[138:141], v[68:71], v[178:181], v[138:141]
	v_mfma_i32_16x16x64_i8 v[126:129], v[56:59], v[186:189], v[126:129]
	v_mfma_i32_16x16x64_i8 v[122:125], v[68:71], v[186:189], v[122:125]
	v_mfma_i32_16x16x64_i8 v[110:113], v[56:59], v[198:201], v[110:113]
	v_mfma_i32_16x16x64_i8 v[106:109], v[68:71], v[198:201], v[106:109]
	v_mfma_i32_16x16x64_i8 v[92:95], v[56:59], v[206:209], v[92:95]
	v_mfma_i32_16x16x64_i8 v[88:91], v[68:71], v[206:209], v[88:91]
	v_mfma_i32_16x16x64_i8 v[142:145], v[60:63], v[182:185], v[142:145]
	v_mfma_i32_16x16x64_i8 v[138:141], v[72:75], v[182:185], v[138:141]
	v_mfma_i32_16x16x64_i8 v[126:129], v[60:63], v[190:193], v[126:129]
	v_mfma_i32_16x16x64_i8 v[122:125], v[72:75], v[190:193], v[122:125]
	v_mfma_i32_16x16x64_i8 v[110:113], v[60:63], v[202:205], v[110:113]
	v_mfma_i32_16x16x64_i8 v[106:109], v[72:75], v[202:205], v[106:109]
	v_mfma_i32_16x16x64_i8 v[92:95], v[60:63], v[210:213], v[92:95]
	v_mfma_i32_16x16x64_i8 v[88:91], v[72:75], v[210:213], v[88:91]
	s_setprio 0
	s_setprio 1
	v_mfma_i32_16x16x64_i8 v[134:137], v[158:161], v[178:181], v[134:137]
	v_mfma_i32_16x16x64_i8 v[130:133], v[170:173], v[178:181], v[130:133]
	v_mfma_i32_16x16x64_i8 v[118:121], v[158:161], v[186:189], v[118:121]
	v_mfma_i32_16x16x64_i8 v[114:117], v[170:173], v[186:189], v[114:117]
	v_mfma_i32_16x16x64_i8 v[102:105], v[158:161], v[198:201], v[102:105]
	v_mfma_i32_16x16x64_i8 v[98:101], v[170:173], v[198:201], v[98:101]
	v_mfma_i32_16x16x64_i8 v[84:87], v[158:161], v[206:209], v[84:87]
	v_mfma_i32_16x16x64_i8 v[80:83], v[170:173], v[206:209], v[80:83]
	v_mfma_i32_16x16x64_i8 v[134:137], v[162:165], v[182:185], v[134:137]
	v_mfma_i32_16x16x64_i8 v[130:133], v[174:177], v[182:185], v[130:133]
	v_mfma_i32_16x16x64_i8 v[118:121], v[162:165], v[190:193], v[118:121]
	v_mfma_i32_16x16x64_i8 v[114:117], v[174:177], v[190:193], v[114:117]
	v_mfma_i32_16x16x64_i8 v[102:105], v[162:165], v[202:205], v[102:105]
	v_mfma_i32_16x16x64_i8 v[98:101], v[174:177], v[202:205], v[98:101]
	v_mfma_i32_16x16x64_i8 v[84:87], v[162:165], v[210:213], v[84:87]
	v_mfma_i32_16x16x64_i8 v[80:83], v[174:177], v[210:213], v[80:83]
	s_setprio 0
	s_barrier
	s_add_i32 s26, s68, s56
	v_lshl_add_u64 v[214:215], v[214:215], 0, s[90:91]
	s_mov_b32 m0, s26
	ds_read_b128 v[178:181], v169 offset:49152
	ds_read_b128 v[182:185], v169 offset:50176
	ds_read_b128 v[186:189], v169 offset:51200
	ds_read_b128 v[190:193], v169 offset:52224
	ds_read_b128 v[198:201], v169 offset:53248
	ds_read_b128 v[202:205], v169 offset:54272
	ds_read_b128 v[206:209], v169 offset:55296
	ds_read_b128 v[210:213], v169 offset:56320
	global_load_lds_dwordx4 v[214:215], off
	s_add_i32 m0, s26, 0x2000
	s_add_u32 s26, s50, 0x10080
	v_lshl_add_u64 v[214:215], v[216:217], 0, s[90:91]
	s_addc_u32 s27, s51, 0
	s_add_i32 s50, s69, s56
	global_load_lds_dwordx4 v[214:215], off
	v_lshl_add_u64 v[214:215], s[26:27], 0, v[150:151]
	s_mov_b32 m0, s50
	s_nop 0
	global_load_lds_dwordx4 v[214:215], off
	v_lshl_add_u64 v[214:215], s[26:27], 0, v[146:147]
	s_add_i32 m0, s50, 0x2000
	s_nop 0
	global_load_lds_dwordx4 v[214:215], off
	v_lshl_add_u64 v[214:215], v[218:219], 0, s[90:91]
	s_mov_b32 m0, s4
	s_nop 0
	global_load_lds_dwordx4 v[214:215], off
	v_lshl_add_u64 v[214:215], v[220:221], 0, s[90:91]
	s_mov_b32 m0, s60
	s_nop 0
	global_load_lds_dwordx4 v[214:215], off
	s_waitcnt vmcnt(8)
	s_waitcnt lgkmcnt(0)
	s_barrier
	s_setprio 1
	s_waitcnt lgkmcnt(0)
	v_mfma_i32_16x16x64_i8 v[76:79], v[56:59], v[178:181], v[76:79]
	v_mfma_i32_16x16x64_i8 v[64:67], v[68:71], v[178:181], v[64:67]
	v_mfma_i32_16x16x64_i8 v[44:47], v[56:59], v[186:189], v[44:47]
	v_mfma_i32_16x16x64_i8 v[40:43], v[68:71], v[186:189], v[40:43]
	v_mfma_i32_16x16x64_i8 v[28:31], v[56:59], v[198:201], v[28:31]
	v_mfma_i32_16x16x64_i8 v[24:27], v[68:71], v[198:201], v[24:27]
	v_mfma_i32_16x16x64_i8 v[12:15], v[56:59], v[206:209], v[12:15]
	v_mfma_i32_16x16x64_i8 v[8:11], v[68:71], v[206:209], v[8:11]
	v_mfma_i32_16x16x64_i8 v[76:79], v[60:63], v[182:185], v[76:79]
	v_mfma_i32_16x16x64_i8 v[64:67], v[72:75], v[182:185], v[64:67]
	v_mfma_i32_16x16x64_i8 v[44:47], v[60:63], v[190:193], v[44:47]
	v_mfma_i32_16x16x64_i8 v[40:43], v[72:75], v[190:193], v[40:43]
	v_mfma_i32_16x16x64_i8 v[28:31], v[60:63], v[202:205], v[28:31]
	v_mfma_i32_16x16x64_i8 v[24:27], v[72:75], v[202:205], v[24:27]
	v_mfma_i32_16x16x64_i8 v[12:15], v[60:63], v[210:213], v[12:15]
	v_mfma_i32_16x16x64_i8 v[8:11], v[72:75], v[210:213], v[8:11]
	s_setprio 0
	s_setprio 1
	v_mfma_i32_16x16x64_i8 v[52:55], v[158:161], v[178:181], v[52:55]
	v_mfma_i32_16x16x64_i8 v[48:51], v[170:173], v[178:181], v[48:51]
	v_mfma_i32_16x16x64_i8 v[36:39], v[158:161], v[186:189], v[36:39]
	v_mfma_i32_16x16x64_i8 v[32:35], v[170:173], v[186:189], v[32:35]
	v_mfma_i32_16x16x64_i8 v[20:23], v[158:161], v[198:201], v[20:23]
	v_mfma_i32_16x16x64_i8 v[16:19], v[170:173], v[198:201], v[16:19]
	v_mfma_i32_16x16x64_i8 v[4:7], v[158:161], v[206:209], v[4:7]
	v_mfma_i32_16x16x64_i8 v[0:3], v[170:173], v[206:209], v[0:3]
	v_mfma_i32_16x16x64_i8 v[52:55], v[162:165], v[182:185], v[52:55]
	v_mfma_i32_16x16x64_i8 v[48:51], v[174:177], v[182:185], v[48:51]
	v_mfma_i32_16x16x64_i8 v[36:39], v[162:165], v[190:193], v[36:39]
	v_mfma_i32_16x16x64_i8 v[32:35], v[174:177], v[190:193], v[32:35]
	v_mfma_i32_16x16x64_i8 v[20:23], v[162:165], v[202:205], v[20:23]
	v_mfma_i32_16x16x64_i8 v[16:19], v[174:177], v[202:205], v[16:19]
	v_mfma_i32_16x16x64_i8 v[4:7], v[162:165], v[210:213], v[4:7]
	v_mfma_i32_16x16x64_i8 v[0:3], v[174:177], v[210:213], v[0:3]
	s_setprio 0
	s_barrier
	s_add_i32 s67, s67, 2
	s_add_u32 s48, s48, 0x100
	s_addc_u32 s49, s49, 0
	s_add_u32 s65, s65, 0x100
	s_addc_u32 s66, s66, 0
	s_cmp_gt_u32 s67, 13
	s_cbranch_scc0 .LBB0_309
	s_and_b64 vcc, exec, s[14:15]
	s_cbranch_vccz .LBB0_312
	s_barrier
.LBB0_312:
	v_lshl_or_b32 v160, s47, 8, v168
	v_lshl_add_u32 v162, s46, 7, v97
	v_ashrrev_i32_e32 v161, 31, v160
	v_ashrrev_i32_e32 v163, 31, v162
	v_lshl_add_u64 v[60:61], v[160:161], 2, s[12:13]
	v_lshl_add_u64 v[164:165], v[162:163], 2, s[10:11]
	v_bfe_u32 v176, v162, 3, 1
	v_lshl_add_u32 v160, v176, 5, v160
	v_and_b32_e32 v162, -9, v162
	s_mov_b32 s100, 0x4c000
	s_mov_b32 s101, 0
	global_load_dwordx4 v[68:71], v[60:61], off offset:16
	global_load_dwordx4 v[72:75], v[60:61], off
	global_load_dwordx4 v[56:59], v[60:61], off offset:144
	s_nop 0
	global_load_dwordx4 v[60:63], v[60:61], off offset:128
	v_cvt_f32_i32_e32 v143, v143
	global_load_dword v170, v[164:165], off
	global_load_dword v166, v[164:165], off offset:64
	v_cvt_f32_i32_e32 v142, v142
	v_cvt_f32_i32_e32 v145, v145
	v_cvt_f32_i32_e32 v144, v144
	v_cvt_f32_i32_e32 v139, v139
	v_cvt_f32_i32_e32 v138, v138
	v_cvt_f32_i32_e32 v141, v141
	v_cvt_f32_i32_e32 v140, v140
	v_mov_b64_e32 v[158:159], s[8:9]
	v_cvt_f32_i32_e32 v135, v135
	v_cvt_f32_i32_e32 v134, v134
	v_cvt_f32_i32_e32 v137, v137
	v_cvt_f32_i32_e32 v136, v136
	v_mad_i64_i32 v[172:173], s[26:27], v162, s21, v[158:159]
	v_lshlrev_b64 v[160:161], 1, v[160:161]
	v_cvt_f32_i32_e32 v131, v131
	v_cvt_f32_i32_e32 v130, v130
	v_cvt_f32_i32_e32 v133, v133
	v_cvt_f32_i32_e32 v132, v132
	v_lshl_add_u64 v[172:173], v[172:173], 0, v[160:161]
	v_cvt_f32_i32_e32 v127, v127
	v_cvt_f32_i32_e32 v126, v126
	v_cvt_f32_i32_e32 v129, v129
	v_cvt_f32_i32_e32 v128, v128
	v_cvt_f32_i32_e32 v123, v123
	v_cvt_f32_i32_e32 v122, v122
	v_cvt_f32_i32_e32 v125, v125
	v_cvt_f32_i32_e32 v124, v124
	v_cvt_f32_i32_e32 v119, v119
	v_cvt_f32_i32_e32 v118, v118
	v_cvt_f32_i32_e32 v121, v121
	v_cvt_f32_i32_e32 v120, v120
	v_cvt_f32_i32_e32 v115, v115
	v_cvt_f32_i32_e32 v114, v114
	v_cvt_f32_i32_e32 v117, v117
	v_cvt_f32_i32_e32 v116, v116
	v_cvt_f32_i32_e32 v111, v111
	v_cvt_f32_i32_e32 v110, v110
	v_cvt_f32_i32_e32 v113, v113
	v_cvt_f32_i32_e32 v112, v112
	v_cvt_f32_i32_e32 v107, v107
	v_cvt_f32_i32_e32 v106, v106
	v_cvt_f32_i32_e32 v109, v109
	v_cvt_f32_i32_e32 v108, v108
	v_cvt_f32_i32_e32 v103, v103
	v_cvt_f32_i32_e32 v102, v102
	v_cvt_f32_i32_e32 v105, v105
	v_cvt_f32_i32_e32 v104, v104
	v_cvt_f32_i32_e32 v99, v99
	v_cvt_f32_i32_e32 v98, v98
	v_cvt_f32_i32_e32 v101, v101
	v_cvt_f32_i32_e32 v100, v100
	v_cvt_f32_i32_e32 v93, v93
	v_cvt_f32_i32_e32 v92, v92
	v_cvt_f32_i32_e32 v95, v95
	v_cvt_f32_i32_e32 v94, v94
	v_cvt_f32_i32_e32 v89, v89
	v_cvt_f32_i32_e32 v88, v88
	v_cvt_f32_i32_e32 v91, v91
	v_cvt_f32_i32_e32 v90, v90
	v_cvt_f32_i32_e32 v85, v85
	v_cvt_f32_i32_e32 v84, v84
	v_cvt_f32_i32_e32 v87, v87
	v_cvt_f32_i32_e32 v86, v86
	v_cvt_f32_i32_e32 v81, v81
	v_cvt_f32_i32_e32 v80, v80
	v_cvt_f32_i32_e32 v83, v83
	v_cvt_f32_i32_e32 v82, v82
	v_cvt_f32_i32_e32 v77, v77
	v_cvt_f32_i32_e32 v76, v76
	v_cvt_f32_i32_e32 v79, v79
	v_cvt_f32_i32_e32 v78, v78
	v_cvt_f32_i32_e32 v65, v65
	v_cvt_f32_i32_e32 v64, v64
	v_cvt_f32_i32_e32 v67, v67
	v_cvt_f32_i32_e32 v66, v66
	v_cvt_f32_i32_e32 v53, v53
	v_cvt_f32_i32_e32 v52, v52
	s_waitcnt vmcnt(0)
	v_pk_mul_f32 v[174:175], v[72:73], v[170:171] op_sel_hi:[1,0]
	v_pk_mul_f32 v[176:177], v[74:75], v[170:171] op_sel_hi:[1,0]
	v_pk_mul_f32 v[142:143], v[174:175], v[142:143]
	v_pk_mul_f32 v[144:145], v[176:177], v[144:145]
	v_pk_mul_f32 v[174:175], v[68:69], v[170:171] op_sel_hi:[1,0]
	v_pk_mul_f32 v[176:177], v[70:71], v[170:171] op_sel_hi:[1,0]
	v_cvt_f32_i32_e32 v55, v55
	v_pk_mul_f32 v[176:177], v[176:177], v[140:141]
	v_pk_mul_f32 v[140:141], v[174:175], v[138:139]
	v_cvt_pk_bf16_f32 v138, v142, v143
	v_cvt_pk_bf16_f32 v139, v144, v145
	v_cvt_f32_i32_e32 v54, v54
	v_cvt_pk_bf16_f32 v140, v140, v141
	v_cvt_pk_bf16_f32 v141, v176, v177
	v_mov_b32_e32 v178, v138
	v_mov_b32_e32 v179, v139
	v_mov_b32_e32 v180, v140
	v_mov_b32_e32 v181, v141
	v_mov_b32_dpp v182, v138 row_ror:8 row_mask:0xf bank_mask:0xf
	v_mov_b32_dpp v183, v139 row_ror:8 row_mask:0xf bank_mask:0xf
	v_mov_b32_dpp v184, v140 row_ror:8 row_mask:0xf bank_mask:0xf
	v_mov_b32_dpp v185, v141 row_ror:8 row_mask:0xf bank_mask:0xf
	v_cvt_f32_i32_e32 v49, v49
	v_cvt_f32_i32_e32 v48, v48
	v_pk_mul_f32 v[138:139], v[60:61], v[170:171] op_sel_hi:[1,0]
	v_pk_mul_f32 v[140:141], v[62:63], v[170:171] op_sel_hi:[1,0]
	v_pk_mul_f32 v[134:135], v[138:139], v[134:135]
	v_pk_mul_f32 v[136:137], v[140:141], v[136:137]
	v_pk_mul_f32 v[138:139], v[56:57], v[170:171] op_sel_hi:[1,0]
	v_pk_mul_f32 v[140:141], v[58:59], v[170:171] op_sel_hi:[1,0]
	v_cvt_f32_i32_e32 v51, v51
	v_pk_mul_f32 v[140:141], v[140:141], v[132:133]
	v_pk_mul_f32 v[132:133], v[138:139], v[130:131]
	v_cvt_pk_bf16_f32 v130, v134, v135
	v_cvt_pk_bf16_f32 v131, v136, v137
	v_pk_mul_f32 v[134:135], v[72:73], v[166:167] op_sel_hi:[1,0]
	v_cvt_pk_bf16_f32 v132, v132, v133
	v_cvt_pk_bf16_f32 v133, v140, v141
	s_nop 1
	v_mov_b32_dpp v178, v130 row_ror:8 row_mask:0xf bank_mask:0xc
	v_mov_b32_dpp v179, v131 row_ror:8 row_mask:0xf bank_mask:0xc
	v_mov_b32_dpp v180, v132 row_ror:8 row_mask:0xf bank_mask:0xc
	v_mov_b32_dpp v181, v133 row_ror:8 row_mask:0xf bank_mask:0xc
	v_lshl_add_u64 v[190:191], v[172:173], 0, s[100:101]
	global_store_dwordx4 v[172:173], v[178:181], off
	v_mov_b32_dpp v130, v182 quad_perm:[0,1,2,3] row_mask:0xf bank_mask:0x3
	v_mov_b32_dpp v131, v183 quad_perm:[0,1,2,3] row_mask:0xf bank_mask:0x3
	v_mov_b32_dpp v132, v184 quad_perm:[0,1,2,3] row_mask:0xf bank_mask:0x3
	v_mov_b32_dpp v133, v185 quad_perm:[0,1,2,3] row_mask:0xf bank_mask:0x3
	global_store_dwordx4 v[190:191], v[130:133], off
	v_pk_mul_f32 v[136:137], v[74:75], v[166:167] op_sel_hi:[1,0]
	v_pk_mul_f32 v[126:127], v[134:135], v[126:127]
	v_or_b32_e32 v130, 16, v162
	v_mad_i64_i32 v[130:131], s[26:27], v130, s21, v[158:159]
	v_lshl_add_u64 v[132:133], v[130:131], 0, v[160:161]
	global_load_dword v130, v[164:165], off offset:128
	v_pk_mul_f32 v[128:129], v[136:137], v[128:129]
	v_pk_mul_f32 v[134:135], v[68:69], v[166:167] op_sel_hi:[1,0]
	v_pk_mul_f32 v[136:137], v[70:71], v[166:167] op_sel_hi:[1,0]
	v_cvt_f32_i32_e32 v50, v50
	v_pk_mul_f32 v[136:137], v[136:137], v[124:125]
	v_pk_mul_f32 v[124:125], v[134:135], v[122:123]
	v_cvt_pk_bf16_f32 v122, v126, v127
	v_cvt_pk_bf16_f32 v123, v128, v129
	v_cvt_f32_i32_e32 v45, v45
	v_cvt_pk_bf16_f32 v124, v124, v125
	v_cvt_pk_bf16_f32 v125, v136, v137
	v_mov_b32_e32 v178, v122
	v_mov_b32_e32 v179, v123
	v_mov_b32_e32 v180, v124
	v_mov_b32_e32 v181, v125
	v_mov_b32_dpp v182, v122 row_ror:8 row_mask:0xf bank_mask:0xf
	v_mov_b32_dpp v183, v123 row_ror:8 row_mask:0xf bank_mask:0xf
	v_mov_b32_dpp v184, v124 row_ror:8 row_mask:0xf bank_mask:0xf
	v_mov_b32_dpp v185, v125 row_ror:8 row_mask:0xf bank_mask:0xf
	v_cvt_f32_i32_e32 v44, v44
	v_cvt_f32_i32_e32 v47, v47
	v_pk_mul_f32 v[122:123], v[60:61], v[166:167] op_sel_hi:[1,0]
	v_pk_mul_f32 v[124:125], v[62:63], v[166:167] op_sel_hi:[1,0]
	v_pk_mul_f32 v[118:119], v[122:123], v[118:119]
	v_pk_mul_f32 v[120:121], v[124:125], v[120:121]
	v_pk_mul_f32 v[122:123], v[56:57], v[166:167] op_sel_hi:[1,0]
	v_pk_mul_f32 v[124:125], v[58:59], v[166:167] op_sel_hi:[1,0]
	v_cvt_f32_i32_e32 v46, v46
	v_pk_mul_f32 v[124:125], v[124:125], v[116:117]
	v_pk_mul_f32 v[116:117], v[122:123], v[114:115]
	v_cvt_pk_bf16_f32 v114, v118, v119
	v_cvt_pk_bf16_f32 v115, v120, v121
	v_cvt_f32_i32_e32 v41, v41
	v_cvt_pk_bf16_f32 v116, v116, v117
	v_cvt_pk_bf16_f32 v117, v124, v125
	s_nop 1
	v_mov_b32_dpp v178, v114 row_ror:8 row_mask:0xf bank_mask:0xc
	v_mov_b32_dpp v179, v115 row_ror:8 row_mask:0xf bank_mask:0xc
	v_mov_b32_dpp v180, v116 row_ror:8 row_mask:0xf bank_mask:0xc
	v_mov_b32_dpp v181, v117 row_ror:8 row_mask:0xf bank_mask:0xc
	v_lshl_add_u64 v[190:191], v[132:133], 0, s[100:101]
	global_store_dwordx4 v[132:133], v[178:181], off
	v_mov_b32_dpp v114, v182 quad_perm:[0,1,2,3] row_mask:0xf bank_mask:0x3
	v_mov_b32_dpp v115, v183 quad_perm:[0,1,2,3] row_mask:0xf bank_mask:0x3
	v_mov_b32_dpp v116, v184 quad_perm:[0,1,2,3] row_mask:0xf bank_mask:0x3
	v_mov_b32_dpp v117, v185 quad_perm:[0,1,2,3] row_mask:0xf bank_mask:0x3
	global_store_dwordx4 v[190:191], v[114:117], off
	v_cvt_f32_i32_e32 v40, v40
	v_cvt_f32_i32_e32 v43, v43
	v_or_b32_e32 v114, 32, v162
	v_mad_i64_i32 v[114:115], s[26:27], v114, s21, v[158:159]
	v_lshl_add_u64 v[116:117], v[114:115], 0, v[160:161]
	global_load_dword v114, v[164:165], off offset:192
	v_cvt_f32_i32_e32 v42, v42
	v_cvt_f32_i32_e32 v37, v37
	v_cvt_f32_i32_e32 v36, v36
	v_cvt_f32_i32_e32 v39, v39
	v_cvt_f32_i32_e32 v38, v38
	v_cvt_f32_i32_e32 v33, v33
	v_cvt_f32_i32_e32 v32, v32
	v_cvt_f32_i32_e32 v35, v35
	v_cvt_f32_i32_e32 v34, v34
	v_cvt_f32_i32_e32 v29, v29
	v_cvt_f32_i32_e32 v28, v28
	v_cvt_f32_i32_e32 v31, v31
	v_cvt_f32_i32_e32 v30, v30
	v_cvt_f32_i32_e32 v25, v25
	v_cvt_f32_i32_e32 v24, v24
	v_cvt_f32_i32_e32 v27, v27
	v_cvt_f32_i32_e32 v26, v26
	v_cvt_f32_i32_e32 v21, v21
	v_cvt_f32_i32_e32 v20, v20
	v_cvt_f32_i32_e32 v23, v23
	v_cvt_f32_i32_e32 v22, v22
	v_cvt_f32_i32_e32 v17, v17
	v_cvt_f32_i32_e32 v16, v16
	v_cvt_f32_i32_e32 v19, v19
	v_cvt_f32_i32_e32 v18, v18
	v_cvt_f32_i32_e32 v13, v13
	v_cvt_f32_i32_e32 v12, v12
	v_cvt_f32_i32_e32 v15, v15
	v_cvt_f32_i32_e32 v14, v14
	v_cvt_f32_i32_e32 v9, v9
	v_cvt_f32_i32_e32 v8, v8
	v_cvt_f32_i32_e32 v11, v11
	v_cvt_f32_i32_e32 v10, v10
	v_cvt_f32_i32_e32 v5, v5
	v_cvt_f32_i32_e32 v4, v4
	v_cvt_f32_i32_e32 v7, v7
	v_cvt_f32_i32_e32 v6, v6
	v_cvt_f32_i32_e32 v1, v1
	v_cvt_f32_i32_e32 v0, v0
	v_cvt_f32_i32_e32 v3, v3
	v_cvt_f32_i32_e32 v2, v2
	s_mov_b64 s[46:47], -1
	s_andn2_b64 vcc, exec, s[40:41]
	s_waitcnt vmcnt(3)
	v_pk_mul_f32 v[118:119], v[72:73], v[130:131] op_sel_hi:[1,0]
	v_pk_mul_f32 v[120:121], v[74:75], v[130:131] op_sel_hi:[1,0]
	v_pk_mul_f32 v[110:111], v[118:119], v[110:111]
	v_pk_mul_f32 v[112:113], v[120:121], v[112:113]
	v_pk_mul_f32 v[118:119], v[68:69], v[130:131] op_sel_hi:[1,0]
	v_pk_mul_f32 v[120:121], v[70:71], v[130:131] op_sel_hi:[1,0]
	s_mov_b64 s[68:69], 0x4000
	v_pk_mul_f32 v[120:121], v[120:121], v[108:109]
	v_pk_mul_f32 v[108:109], v[118:119], v[106:107]
	v_cvt_pk_bf16_f32 v106, v110, v111
	v_cvt_pk_bf16_f32 v107, v112, v113
	s_mov_b64 s[64:65], 0xfff
	v_cvt_pk_bf16_f32 v108, v108, v109
	v_cvt_pk_bf16_f32 v109, v120, v121
	v_mov_b32_e32 v178, v106
	v_mov_b32_e32 v179, v107
	v_mov_b32_e32 v180, v108
	v_mov_b32_e32 v181, v109
	v_mov_b32_dpp v182, v106 row_ror:8 row_mask:0xf bank_mask:0xf
	v_mov_b32_dpp v183, v107 row_ror:8 row_mask:0xf bank_mask:0xf
	v_mov_b32_dpp v184, v108 row_ror:8 row_mask:0xf bank_mask:0xf
	v_mov_b32_dpp v185, v109 row_ror:8 row_mask:0xf bank_mask:0xf
	s_nop 1
	v_pk_mul_f32 v[106:107], v[60:61], v[130:131] op_sel_hi:[1,0]
	v_pk_mul_f32 v[108:109], v[62:63], v[130:131] op_sel_hi:[1,0]
	v_pk_mul_f32 v[102:103], v[106:107], v[102:103]
	v_pk_mul_f32 v[104:105], v[108:109], v[104:105]
	v_pk_mul_f32 v[106:107], v[56:57], v[130:131] op_sel_hi:[1,0]
	v_pk_mul_f32 v[108:109], v[58:59], v[130:131] op_sel_hi:[1,0]
	s_nop 0
	v_pk_mul_f32 v[108:109], v[108:109], v[100:101]
	v_pk_mul_f32 v[100:101], v[106:107], v[98:99]
	v_cvt_pk_bf16_f32 v98, v102, v103
	v_cvt_pk_bf16_f32 v99, v104, v105
	s_waitcnt vmcnt(0)
	v_pk_mul_f32 v[102:103], v[72:73], v[114:115] op_sel_hi:[1,0]
	v_cvt_pk_bf16_f32 v100, v100, v101
	v_cvt_pk_bf16_f32 v101, v108, v109
	s_nop 1
	v_mov_b32_dpp v178, v98 row_ror:8 row_mask:0xf bank_mask:0xc
	v_mov_b32_dpp v179, v99 row_ror:8 row_mask:0xf bank_mask:0xc
	v_mov_b32_dpp v180, v100 row_ror:8 row_mask:0xf bank_mask:0xc
	v_mov_b32_dpp v181, v101 row_ror:8 row_mask:0xf bank_mask:0xc
	v_lshl_add_u64 v[190:191], v[116:117], 0, s[100:101]
	global_store_dwordx4 v[116:117], v[178:181], off
	v_mov_b32_dpp v98, v182 quad_perm:[0,1,2,3] row_mask:0xf bank_mask:0x3
	v_mov_b32_dpp v99, v183 quad_perm:[0,1,2,3] row_mask:0xf bank_mask:0x3
	v_mov_b32_dpp v100, v184 quad_perm:[0,1,2,3] row_mask:0xf bank_mask:0x3
	v_mov_b32_dpp v101, v185 quad_perm:[0,1,2,3] row_mask:0xf bank_mask:0x3
	global_store_dwordx4 v[190:191], v[98:101], off
	v_pk_mul_f32 v[104:105], v[74:75], v[114:115] op_sel_hi:[1,0]
	v_pk_mul_f32 v[92:93], v[102:103], v[92:93]
	v_or_b32_e32 v98, 48, v162
	v_mad_i64_i32 v[98:99], s[26:27], v98, s21, v[158:159]
	v_lshl_add_u64 v[100:101], v[98:99], 0, v[160:161]
	global_load_dword v98, v[164:165], off offset:512
	v_pk_mul_f32 v[94:95], v[104:105], v[94:95]
	v_pk_mul_f32 v[102:103], v[68:69], v[114:115] op_sel_hi:[1,0]
	v_pk_mul_f32 v[104:105], v[70:71], v[114:115] op_sel_hi:[1,0]
	s_nop 0
	v_pk_mul_f32 v[104:105], v[104:105], v[90:91]
	v_pk_mul_f32 v[90:91], v[102:103], v[88:89]
	v_cvt_pk_bf16_f32 v88, v92, v93
	v_cvt_pk_bf16_f32 v89, v94, v95
	s_nop 0
	v_cvt_pk_bf16_f32 v90, v90, v91
	v_cvt_pk_bf16_f32 v91, v104, v105
	v_mov_b32_e32 v178, v88
	v_mov_b32_e32 v179, v89
	v_mov_b32_e32 v180, v90
	v_mov_b32_e32 v181, v91
	v_mov_b32_dpp v182, v88 row_ror:8 row_mask:0xf bank_mask:0xf
	v_mov_b32_dpp v183, v89 row_ror:8 row_mask:0xf bank_mask:0xf
	v_mov_b32_dpp v184, v90 row_ror:8 row_mask:0xf bank_mask:0xf
	v_mov_b32_dpp v185, v91 row_ror:8 row_mask:0xf bank_mask:0xf
	s_nop 1
	v_pk_mul_f32 v[88:89], v[60:61], v[114:115] op_sel_hi:[1,0]
	v_pk_mul_f32 v[90:91], v[62:63], v[114:115] op_sel_hi:[1,0]
	v_pk_mul_f32 v[84:85], v[88:89], v[84:85]
	v_pk_mul_f32 v[86:87], v[90:91], v[86:87]
	v_pk_mul_f32 v[88:89], v[56:57], v[114:115] op_sel_hi:[1,0]
	v_pk_mul_f32 v[90:91], v[58:59], v[114:115] op_sel_hi:[1,0]
	s_nop 0
	v_pk_mul_f32 v[90:91], v[90:91], v[82:83]
	v_pk_mul_f32 v[82:83], v[88:89], v[80:81]
	v_cvt_pk_bf16_f32 v80, v84, v85
	v_cvt_pk_bf16_f32 v81, v86, v87
	s_waitcnt vmcnt(0)
	v_pk_mul_f32 v[84:85], v[72:73], v[98:99] op_sel_hi:[1,0]
	v_cvt_pk_bf16_f32 v82, v82, v83
	v_cvt_pk_bf16_f32 v83, v90, v91
	s_nop 1
	v_mov_b32_dpp v178, v80 row_ror:8 row_mask:0xf bank_mask:0xc
	v_mov_b32_dpp v179, v81 row_ror:8 row_mask:0xf bank_mask:0xc
	v_mov_b32_dpp v180, v82 row_ror:8 row_mask:0xf bank_mask:0xc
	v_mov_b32_dpp v181, v83 row_ror:8 row_mask:0xf bank_mask:0xc
	v_lshl_add_u64 v[190:191], v[100:101], 0, s[100:101]
	global_store_dwordx4 v[100:101], v[178:181], off
	v_mov_b32_dpp v80, v182 quad_perm:[0,1,2,3] row_mask:0xf bank_mask:0x3
	v_mov_b32_dpp v81, v183 quad_perm:[0,1,2,3] row_mask:0xf bank_mask:0x3
	v_mov_b32_dpp v82, v184 quad_perm:[0,1,2,3] row_mask:0xf bank_mask:0x3
	v_mov_b32_dpp v83, v185 quad_perm:[0,1,2,3] row_mask:0xf bank_mask:0x3
	global_store_dwordx4 v[190:191], v[80:83], off
	v_pk_mul_f32 v[86:87], v[74:75], v[98:99] op_sel_hi:[1,0]
	v_pk_mul_f32 v[76:77], v[84:85], v[76:77]
	v_add_u32_e32 v80, 0x80, v162
	v_mad_i64_i32 v[80:81], s[26:27], v80, s21, v[158:159]
	v_lshl_add_u64 v[82:83], v[80:81], 0, v[160:161]
	global_load_dword v80, v[164:165], off offset:576
	v_pk_mul_f32 v[78:79], v[86:87], v[78:79]
	v_pk_mul_f32 v[84:85], v[68:69], v[98:99] op_sel_hi:[1,0]
	v_pk_mul_f32 v[86:87], v[70:71], v[98:99] op_sel_hi:[1,0]
	s_nop 0
	v_pk_mul_f32 v[86:87], v[86:87], v[66:67]
	v_pk_mul_f32 v[66:67], v[84:85], v[64:65]
	v_cvt_pk_bf16_f32 v64, v76, v77
	v_cvt_pk_bf16_f32 v65, v78, v79
	s_nop 0
	v_cvt_pk_bf16_f32 v66, v66, v67
	v_cvt_pk_bf16_f32 v67, v86, v87
	v_mov_b32_e32 v178, v64
	v_mov_b32_e32 v179, v65
	v_mov_b32_e32 v180, v66
	v_mov_b32_e32 v181, v67
	v_mov_b32_dpp v182, v64 row_ror:8 row_mask:0xf bank_mask:0xf
	v_mov_b32_dpp v183, v65 row_ror:8 row_mask:0xf bank_mask:0xf
	v_mov_b32_dpp v184, v66 row_ror:8 row_mask:0xf bank_mask:0xf
	v_mov_b32_dpp v185, v67 row_ror:8 row_mask:0xf bank_mask:0xf
	s_nop 1
	v_pk_mul_f32 v[64:65], v[60:61], v[98:99] op_sel_hi:[1,0]
	v_pk_mul_f32 v[66:67], v[62:63], v[98:99] op_sel_hi:[1,0]
	v_pk_mul_f32 v[52:53], v[64:65], v[52:53]
	v_pk_mul_f32 v[54:55], v[66:67], v[54:55]
	v_pk_mul_f32 v[64:65], v[56:57], v[98:99] op_sel_hi:[1,0]
	v_pk_mul_f32 v[66:67], v[58:59], v[98:99] op_sel_hi:[1,0]
	s_nop 0
	v_pk_mul_f32 v[66:67], v[66:67], v[50:51]
	v_pk_mul_f32 v[50:51], v[64:65], v[48:49]
	v_cvt_pk_bf16_f32 v48, v52, v53
	v_cvt_pk_bf16_f32 v49, v54, v55
	s_waitcnt vmcnt(0)
	v_pk_mul_f32 v[52:53], v[72:73], v[80:81] op_sel_hi:[1,0]
	v_cvt_pk_bf16_f32 v50, v50, v51
	v_cvt_pk_bf16_f32 v51, v66, v67
	s_nop 1
	v_mov_b32_dpp v178, v48 row_ror:8 row_mask:0xf bank_mask:0xc
	v_mov_b32_dpp v179, v49 row_ror:8 row_mask:0xf bank_mask:0xc
	v_mov_b32_dpp v180, v50 row_ror:8 row_mask:0xf bank_mask:0xc
	v_mov_b32_dpp v181, v51 row_ror:8 row_mask:0xf bank_mask:0xc
	v_lshl_add_u64 v[190:191], v[82:83], 0, s[100:101]
	global_store_dwordx4 v[82:83], v[178:181], off
	v_mov_b32_dpp v48, v182 quad_perm:[0,1,2,3] row_mask:0xf bank_mask:0x3
	v_mov_b32_dpp v49, v183 quad_perm:[0,1,2,3] row_mask:0xf bank_mask:0x3
	v_mov_b32_dpp v50, v184 quad_perm:[0,1,2,3] row_mask:0xf bank_mask:0x3
	v_mov_b32_dpp v51, v185 quad_perm:[0,1,2,3] row_mask:0xf bank_mask:0x3
	global_store_dwordx4 v[190:191], v[48:51], off
	v_pk_mul_f32 v[54:55], v[74:75], v[80:81] op_sel_hi:[1,0]
	v_pk_mul_f32 v[44:45], v[52:53], v[44:45]
	v_add_u32_e32 v48, 0x90, v162
	v_mad_i64_i32 v[48:49], s[26:27], v48, s21, v[158:159]
	v_lshl_add_u64 v[50:51], v[48:49], 0, v[160:161]
	global_load_dword v48, v[164:165], off offset:640
	v_pk_mul_f32 v[46:47], v[54:55], v[46:47]
	v_pk_mul_f32 v[52:53], v[68:69], v[80:81] op_sel_hi:[1,0]
	v_pk_mul_f32 v[54:55], v[70:71], v[80:81] op_sel_hi:[1,0]
	s_nop 0
	v_pk_mul_f32 v[54:55], v[54:55], v[42:43]
	v_pk_mul_f32 v[42:43], v[52:53], v[40:41]
	v_cvt_pk_bf16_f32 v40, v44, v45
	v_cvt_pk_bf16_f32 v41, v46, v47
	s_nop 0
	v_cvt_pk_bf16_f32 v42, v42, v43
	v_cvt_pk_bf16_f32 v43, v54, v55
	v_mov_b32_e32 v178, v40
	v_mov_b32_e32 v179, v41
	v_mov_b32_e32 v180, v42
	v_mov_b32_e32 v181, v43
	v_mov_b32_dpp v182, v40 row_ror:8 row_mask:0xf bank_mask:0xf
	v_mov_b32_dpp v183, v41 row_ror:8 row_mask:0xf bank_mask:0xf
	v_mov_b32_dpp v184, v42 row_ror:8 row_mask:0xf bank_mask:0xf
	v_mov_b32_dpp v185, v43 row_ror:8 row_mask:0xf bank_mask:0xf
	s_nop 1
	v_pk_mul_f32 v[40:41], v[60:61], v[80:81] op_sel_hi:[1,0]
	v_pk_mul_f32 v[42:43], v[62:63], v[80:81] op_sel_hi:[1,0]
	v_pk_mul_f32 v[36:37], v[40:41], v[36:37]
	v_pk_mul_f32 v[38:39], v[42:43], v[38:39]
	v_pk_mul_f32 v[40:41], v[56:57], v[80:81] op_sel_hi:[1,0]
	v_pk_mul_f32 v[42:43], v[58:59], v[80:81] op_sel_hi:[1,0]
	s_nop 0
	v_pk_mul_f32 v[42:43], v[42:43], v[34:35]
	v_pk_mul_f32 v[34:35], v[40:41], v[32:33]
	v_cvt_pk_bf16_f32 v32, v36, v37
	v_cvt_pk_bf16_f32 v33, v38, v39
	s_waitcnt vmcnt(0)
	v_pk_mul_f32 v[36:37], v[72:73], v[48:49] op_sel_hi:[1,0]
	v_cvt_pk_bf16_f32 v34, v34, v35
	v_cvt_pk_bf16_f32 v35, v42, v43
	s_nop 1
	v_mov_b32_dpp v178, v32 row_ror:8 row_mask:0xf bank_mask:0xc
	v_mov_b32_dpp v179, v33 row_ror:8 row_mask:0xf bank_mask:0xc
	v_mov_b32_dpp v180, v34 row_ror:8 row_mask:0xf bank_mask:0xc
	v_mov_b32_dpp v181, v35 row_ror:8 row_mask:0xf bank_mask:0xc
	v_lshl_add_u64 v[190:191], v[50:51], 0, s[100:101]
	global_store_dwordx4 v[50:51], v[178:181], off
	v_mov_b32_dpp v32, v182 quad_perm:[0,1,2,3] row_mask:0xf bank_mask:0x3
	v_mov_b32_dpp v33, v183 quad_perm:[0,1,2,3] row_mask:0xf bank_mask:0x3
	v_mov_b32_dpp v34, v184 quad_perm:[0,1,2,3] row_mask:0xf bank_mask:0x3
	v_mov_b32_dpp v35, v185 quad_perm:[0,1,2,3] row_mask:0xf bank_mask:0x3
	global_store_dwordx4 v[190:191], v[32:35], off
	v_pk_mul_f32 v[38:39], v[74:75], v[48:49] op_sel_hi:[1,0]
	v_pk_mul_f32 v[28:29], v[36:37], v[28:29]
	v_add_u32_e32 v32, 0xa0, v162
	v_mad_i64_i32 v[32:33], s[26:27], v32, s21, v[158:159]
	v_lshl_add_u64 v[34:35], v[32:33], 0, v[160:161]
	global_load_dword v32, v[164:165], off offset:704
	v_pk_mul_f32 v[30:31], v[38:39], v[30:31]
	v_pk_mul_f32 v[36:37], v[68:69], v[48:49] op_sel_hi:[1,0]
	v_pk_mul_f32 v[38:39], v[70:71], v[48:49] op_sel_hi:[1,0]
	s_nop 0
	v_pk_mul_f32 v[38:39], v[38:39], v[26:27]
	v_pk_mul_f32 v[26:27], v[36:37], v[24:25]
	v_cvt_pk_bf16_f32 v24, v28, v29
	v_cvt_pk_bf16_f32 v25, v30, v31
	s_nop 0
	v_cvt_pk_bf16_f32 v26, v26, v27
	v_cvt_pk_bf16_f32 v27, v38, v39
	v_mov_b32_e32 v178, v24
	v_mov_b32_e32 v179, v25
	v_mov_b32_e32 v180, v26
	v_mov_b32_e32 v181, v27
	v_mov_b32_dpp v182, v24 row_ror:8 row_mask:0xf bank_mask:0xf
	v_mov_b32_dpp v183, v25 row_ror:8 row_mask:0xf bank_mask:0xf
	v_mov_b32_dpp v184, v26 row_ror:8 row_mask:0xf bank_mask:0xf
	v_mov_b32_dpp v185, v27 row_ror:8 row_mask:0xf bank_mask:0xf
	s_nop 1
	v_pk_mul_f32 v[24:25], v[60:61], v[48:49] op_sel_hi:[1,0]
	v_pk_mul_f32 v[26:27], v[62:63], v[48:49] op_sel_hi:[1,0]
	v_pk_mul_f32 v[20:21], v[24:25], v[20:21]
	v_pk_mul_f32 v[22:23], v[26:27], v[22:23]
	v_pk_mul_f32 v[24:25], v[56:57], v[48:49] op_sel_hi:[1,0]
	v_pk_mul_f32 v[26:27], v[58:59], v[48:49] op_sel_hi:[1,0]
	s_nop 0
	v_pk_mul_f32 v[26:27], v[26:27], v[18:19]
	v_pk_mul_f32 v[18:19], v[24:25], v[16:17]
	v_cvt_pk_bf16_f32 v16, v20, v21
	v_cvt_pk_bf16_f32 v17, v22, v23
	s_waitcnt vmcnt(0)
	v_pk_mul_f32 v[20:21], v[74:75], v[32:33] op_sel_hi:[1,0]
	v_cvt_pk_bf16_f32 v18, v18, v19
	v_cvt_pk_bf16_f32 v19, v26, v27
	s_nop 1
	v_mov_b32_dpp v178, v16 row_ror:8 row_mask:0xf bank_mask:0xc
	v_mov_b32_dpp v179, v17 row_ror:8 row_mask:0xf bank_mask:0xc
	v_mov_b32_dpp v180, v18 row_ror:8 row_mask:0xf bank_mask:0xc
	v_mov_b32_dpp v181, v19 row_ror:8 row_mask:0xf bank_mask:0xc
	v_lshl_add_u64 v[190:191], v[34:35], 0, s[100:101]
	global_store_dwordx4 v[34:35], v[178:181], off
	v_mov_b32_dpp v16, v182 quad_perm:[0,1,2,3] row_mask:0xf bank_mask:0x3
	v_mov_b32_dpp v17, v183 quad_perm:[0,1,2,3] row_mask:0xf bank_mask:0x3
	v_mov_b32_dpp v18, v184 quad_perm:[0,1,2,3] row_mask:0xf bank_mask:0x3
	v_mov_b32_dpp v19, v185 quad_perm:[0,1,2,3] row_mask:0xf bank_mask:0x3
	global_store_dwordx4 v[190:191], v[16:19], off
	v_pk_mul_f32 v[14:15], v[20:21], v[14:15]
	v_pk_mul_f32 v[20:21], v[70:71], v[32:33] op_sel_hi:[1,0]
	v_pk_mul_f32 v[18:19], v[72:73], v[32:33] op_sel_hi:[1,0]
	v_add_u32_e32 v16, 0xb0, v162
	v_pk_mul_f32 v[12:13], v[18:19], v[12:13]
	v_pk_mul_f32 v[18:19], v[68:69], v[32:33] op_sel_hi:[1,0]
	v_mad_i64_i32 v[16:17], s[26:27], v16, s21, v[158:159]
	v_pk_mul_f32 v[20:21], v[20:21], v[10:11]
	v_pk_mul_f32 v[10:11], v[18:19], v[8:9]
	v_lshl_add_u64 v[16:17], v[16:17], 0, v[160:161]
	v_cvt_pk_bf16_f32 v8, v12, v13
	v_cvt_pk_bf16_f32 v9, v14, v15
	v_cvt_pk_bf16_f32 v10, v10, v11
	v_cvt_pk_bf16_f32 v11, v20, v21
	v_mov_b32_e32 v178, v8
	v_mov_b32_e32 v179, v9
	v_mov_b32_e32 v180, v10
	v_mov_b32_e32 v181, v11
	v_mov_b32_dpp v182, v8 row_ror:8 row_mask:0xf bank_mask:0xf
	v_mov_b32_dpp v183, v9 row_ror:8 row_mask:0xf bank_mask:0xf
	v_mov_b32_dpp v184, v10 row_ror:8 row_mask:0xf bank_mask:0xf
	v_mov_b32_dpp v185, v11 row_ror:8 row_mask:0xf bank_mask:0xf
	s_nop 1
	v_pk_mul_f32 v[8:9], v[60:61], v[32:33] op_sel_hi:[1,0]
	v_pk_mul_f32 v[10:11], v[62:63], v[32:33] op_sel_hi:[1,0]
	v_pk_mul_f32 v[4:5], v[8:9], v[4:5]
	v_pk_mul_f32 v[6:7], v[10:11], v[6:7]
	v_pk_mul_f32 v[8:9], v[56:57], v[32:33] op_sel_hi:[1,0]
	v_pk_mul_f32 v[10:11], v[58:59], v[32:33] op_sel_hi:[1,0]
	s_nop 0
	v_pk_mul_f32 v[10:11], v[10:11], v[2:3]
	v_pk_mul_f32 v[2:3], v[8:9], v[0:1]
	v_cvt_pk_bf16_f32 v0, v4, v5
	v_cvt_pk_bf16_f32 v1, v6, v7
	s_nop 0
	v_cvt_pk_bf16_f32 v2, v2, v3
	v_cvt_pk_bf16_f32 v3, v10, v11
	s_nop 1
	v_mov_b32_dpp v178, v0 row_ror:8 row_mask:0xf bank_mask:0xc
	v_mov_b32_dpp v179, v1 row_ror:8 row_mask:0xf bank_mask:0xc
	v_mov_b32_dpp v180, v2 row_ror:8 row_mask:0xf bank_mask:0xc
	v_mov_b32_dpp v181, v3 row_ror:8 row_mask:0xf bank_mask:0xc
	v_lshl_add_u64 v[190:191], v[16:17], 0, s[100:101]
	global_store_dwordx4 v[16:17], v[178:181], off
	v_mov_b32_dpp v0, v182 quad_perm:[0,1,2,3] row_mask:0xf bank_mask:0x3
	v_mov_b32_dpp v1, v183 quad_perm:[0,1,2,3] row_mask:0xf bank_mask:0x3
	v_mov_b32_dpp v2, v184 quad_perm:[0,1,2,3] row_mask:0xf bank_mask:0x3
	v_mov_b32_dpp v3, v185 quad_perm:[0,1,2,3] row_mask:0xf bank_mask:0x3
	global_store_dwordx4 v[190:191], v[0:3], off
	s_cbranch_vccnz .LBB0_305
	s_andn2_b64 vcc, exec, s[6:7]
	s_cbranch_vccnz .LBB0_304
	s_barrier
	s_branch .LBB0_304

	.amdhsa_kernel _Z6mk_fwd4Args
		.amdhsa_group_segment_fixed_size 0
		.amdhsa_private_segment_fixed_size 0
		.amdhsa_kernarg_size 512
		.amdhsa_user_sgpr_count 2
		.amdhsa_user_sgpr_dispatch_ptr 0
		.amdhsa_user_sgpr_queue_ptr 0
		.amdhsa_user_sgpr_kernarg_segment_ptr 1
		.amdhsa_user_sgpr_dispatch_id 0
		.amdhsa_user_sgpr_kernarg_preload_length 0
		.amdhsa_user_sgpr_kernarg_preload_offset 0
		.amdhsa_user_sgpr_private_segment_size 0
		.amdhsa_uses_dynamic_stack 0
		.amdhsa_enable_private_segment 0
		.amdhsa_system_sgpr_workgroup_id_x 1
		.amdhsa_system_sgpr_workgroup_id_y 0
		.amdhsa_system_sgpr_workgroup_id_z 0
		.amdhsa_system_sgpr_workgroup_info 0
		.amdhsa_system_vgpr_workitem_id 0
		.amdhsa_next_free_vgpr 256
		.amdhsa_next_free_sgpr 102
		.amdhsa_accum_offset 256
		.amdhsa_reserve_vcc 1
		.amdhsa_float_round_mode_32 0
		.amdhsa_float_round_mode_16_64 0
		.amdhsa_float_denorm_mode_32 3
		.amdhsa_float_denorm_mode_16_64 3
		.amdhsa_dx10_clamp 1
		.amdhsa_ieee_mode 1
		.amdhsa_fp16_overflow 0
		.amdhsa_tg_split 0
		.amdhsa_exception_fp_ieee_invalid_op 0
		.amdhsa_exception_fp_denorm_src 0
		.amdhsa_exception_fp_ieee_div_zero 0
		.amdhsa_exception_fp_ieee_overflow 0
		.amdhsa_exception_fp_ieee_underflow 0
		.amdhsa_exception_fp_ieee_inexact 0
		.amdhsa_exception_int_div_zero 0
	.end_amdhsa_kernel

amdhsa.kernels:
  - .agpr_count:     0
    .args:
      - .offset:         0
        .size:           256
        .value_kind:     by_value
      - .offset:         256
        .size:           4
        .value_kind:     hidden_block_count_x
      - .offset:         260
        .size:           4
        .value_kind:     hidden_block_count_y
      - .offset:         264
        .size:           4
        .value_kind:     hidden_block_count_z
      - .offset:         268
        .size:           2
        .value_kind:     hidden_group_size_x
      - .offset:         270
        .size:           2
        .value_kind:     hidden_group_size_y
      - .offset:         272
        .size:           2
        .value_kind:     hidden_group_size_z
      - .offset:         274
        .size:           2
        .value_kind:     hidden_remainder_x
      - .offset:         276
        .size:           2
        .value_kind:     hidden_remainder_y
      - .offset:         278
        .size:           2
        .value_kind:     hidden_remainder_z
      - .offset:         296
        .size:           8
        .value_kind:     hidden_global_offset_x
      - .offset:         304
        .size:           8
        .value_kind:     hidden_global_offset_y
      - .offset:         312
        .size:           8
        .value_kind:     hidden_global_offset_z
      - .offset:         320
        .size:           2
        .value_kind:     hidden_grid_dims
      - .offset:         376
        .size:           4
        .value_kind:     hidden_dynamic_lds_size
    .group_segment_fixed_size: 0
    .kernarg_segment_align: 8
    .kernarg_segment_size: 512
    .language:       OpenCL C
    .language_version:
      - 2
      - 0
    .max_flat_workgroup_size: 512
    .name:           _Z6mk_fwd4Args
    .private_segment_fixed_size: 0
    .sgpr_count:     108
    .sgpr_spill_count: 122
    .symbol:         _Z6mk_fwd4Args.kd
    .uniform_work_group_size: 1
    .uses_dynamic_stack: false
    .vgpr_count:     256
    .vgpr_spill_count: 0
    .wavefront_size: 64
